# P5b sample-row 64x32 tiles: A/B rows staged into LDS with 1KB-contiguous LDS-DMA loads in two k-halves, fragments read from padded LDS rows
# speedup vs baseline: 1.0586x; 1.0191x over previous
.Lp1_ld0:
	v_add_u32_e32 v58, 0xffffc000, v30
	v_lshrrev_b32_e32 v58, 2, v58
	v_add_u32_e32 v58, 8, v58
	v_ashrrev_i32_e32 v59, 11, v30
	v_cmp_gt_i32_e64 s[96:97], s53, v30
	v_readlane_b32 s94, v250, 6
	v_readlane_b32 s95, v250, 7
	v_cndmask_b32_e64 v110, v58, v59, s[96:97]
	s_nop 1
	v_mov_b64_e32 v[58:59], s[94:95]
	v_mad_i64_i32 v[58:59], s[96:97], v110, s78, v[58:59]
	v_lshl_add_u64 v[58:59], v[58:59], 0, v[18:19]
	v_lshl_add_u64 v[60:61], v[58:59], 0, s[22:23]
	global_load_dwordx4 v[62:65], v[20:21], off
	global_load_dwordx4 v[66:69], v[20:21], off offset:16
	global_load_dwordx4 v[70:73], v[20:21], off offset:2048
	global_load_dwordx4 v[74:77], v[20:21], off offset:2064
	global_load_dwordx4 v[78:81], v[60:61], off
	global_load_dwordx4 v[82:85], v[60:61], off offset:16
	global_load_dwordx4 v[86:89], v[60:61], off offset:2048
	global_load_dwordx4 v[90:93], v[60:61], off offset:2064
	global_load_dwordx4 v[94:97], v[58:59], off
	global_load_dwordx4 v[98:101], v[58:59], off offset:16
	global_load_dwordx4 v[102:105], v[58:59], off offset:2048
	global_load_dwordx4 v[106:109], v[58:59], off offset:2064

.LBB0_685:
	s_barrier
	v_mov_b32_e32 v0, v154
	s_and_b32 s7, s2, 0xffffffc0
	s_addk_i32 s7, 0x4000
	v_ashrrev_i32_e32 v1, 3, v0
	v_and_b32_e32 v15, -16, v1
	v_and_b32_e32 v14, 15, v0
	v_lshrrev_b32_e32 v17, 4, v0
	v_lshrrev_b32_e32 v1, 2, v0
	v_and_b32_e32 v8, 48, v0
	v_add_u32_e32 v0, s7, v15
	v_or_b32_e32 v0, v0, v14
	v_and_b32_e32 v16, 16, v1
	v_ashrrev_i32_e32 v1, 31, v0
	s_and_b32 s8, s4, 0x3e0
	v_lshlrev_b64 v[0:1], 11, v[0:1]
	v_lshl_add_u64 v[10:11], s[14:15], 0, v[0:1]
	v_or3_b32 v0, s8, v16, v14
	v_lshlrev_b32_e32 v0, 11, v0
	v_mov_b32_e32 v1, v9
	v_lshl_add_u64 v[12:13], s[14:15], 0, v[0:1]
	s_movk_i32 s7, 0xffc0
	v_mov_b32_e32 v0, v9
	v_mov_b32_e32 v2, v9
	v_mov_b32_e32 v3, v9
	v_mov_b32_e32 v4, v9
	v_mov_b32_e32 v5, v9
	v_mov_b32_e32 v6, v9
	v_mov_b32_e32 v7, v9
	s_and_b32 s7, s2, 0xffffffc0
	s_addk_i32 s7, 0x4000
	v_lshrrev_b32_e32 v18, 6, v154
	v_and_b32_e32 v46, 63, v154
	v_lshlrev_b32_e32 v46, 4, v46
	v_mov_b32_e32 v47, 0
	v_readfirstlane_b32 s9, v18
	s_nop 3
	s_lshl_b32 s12, s9, 3
	s_add_u32 s12, s12, s7
	s_lshl_b32 s12, s12, 11
	s_add_u32 s10, s14, 0xd178000
	s_addc_u32 s11, s15, 0
	s_add_u32 s10, s10, s12
	s_addc_u32 s11, s11, 0
	v_lshl_add_u64 v[48:49], v[46:47], 0, s[10:11]
	s_lshl_b32 s12, s9, 2
	s_add_u32 s12, s12, s8
	s_lshl_b32 s12, s12, 11
	s_add_u32 s10, s14, 0xf00000
	s_addc_u32 s11, s15, 0
	s_add_u32 s10, s10, s12
	s_addc_u32 s11, s11, 0
	v_lshl_add_u64 v[50:51], v[46:47], 0, s[10:11]
	v_add_u32_e32 v18, v15, v14
	v_mul_u32_u24_e32 v18, 0x410, v18
	v_add_u32_e32 v44, v18, v8
	v_add_u32_e32 v19, v16, v14
	v_mul_u32_u24_e32 v19, 0x410, v19
	s_mov_b32 s12, 0x10400
	v_add3_u32 v45, v19, v8, s12
	s_mul_i32 s7, s9, 0x2080
	s_mul_i32 s8, s9, 0x1040
	s_add_u32 s8, s8, 0x10400
	s_mov_b32 s10, 0x800
	s_mov_b32 s11, 0
	v_mov_b32_e32 v40, v48
	v_mov_b32_e32 v41, v49
	v_mov_b32_e32 v42, v50
	v_mov_b32_e32 v43, v51
	s_mov_b32 m0, s7
	s_nop 0
	global_load_lds_dwordx4 v[40:41], off
	v_lshl_add_u64 v[40:41], v[40:41], 0, s[10:11]
	s_add_u32 s12, s7, 1040
	s_mov_b32 m0, s12
	s_nop 0
	global_load_lds_dwordx4 v[40:41], off
	v_lshl_add_u64 v[40:41], v[40:41], 0, s[10:11]
	s_add_u32 s12, s7, 2080
	s_mov_b32 m0, s12
	s_nop 0
	global_load_lds_dwordx4 v[40:41], off
	v_lshl_add_u64 v[40:41], v[40:41], 0, s[10:11]
	s_add_u32 s12, s7, 3120
	s_mov_b32 m0, s12
	s_nop 0
	global_load_lds_dwordx4 v[40:41], off
	v_lshl_add_u64 v[40:41], v[40:41], 0, s[10:11]
	s_add_u32 s12, s7, 4160
	s_mov_b32 m0, s12
	s_nop 0
	global_load_lds_dwordx4 v[40:41], off
	v_lshl_add_u64 v[40:41], v[40:41], 0, s[10:11]
	s_add_u32 s12, s7, 5200
	s_mov_b32 m0, s12
	s_nop 0
	global_load_lds_dwordx4 v[40:41], off
	v_lshl_add_u64 v[40:41], v[40:41], 0, s[10:11]
	s_add_u32 s12, s7, 6240
	s_mov_b32 m0, s12
	s_nop 0
	global_load_lds_dwordx4 v[40:41], off
	v_lshl_add_u64 v[40:41], v[40:41], 0, s[10:11]
	s_add_u32 s12, s7, 7280
	s_mov_b32 m0, s12
	s_nop 0
	global_load_lds_dwordx4 v[40:41], off
	s_mov_b32 m0, s8
	s_nop 0
	global_load_lds_dwordx4 v[42:43], off
	v_lshl_add_u64 v[42:43], v[42:43], 0, s[10:11]
	s_add_u32 s12, s8, 1040
	s_mov_b32 m0, s12
	s_nop 0
	global_load_lds_dwordx4 v[42:43], off
	v_lshl_add_u64 v[42:43], v[42:43], 0, s[10:11]
	s_add_u32 s12, s8, 2080
	s_mov_b32 m0, s12
	s_nop 0
	global_load_lds_dwordx4 v[42:43], off
	v_lshl_add_u64 v[42:43], v[42:43], 0, s[10:11]
	s_add_u32 s12, s8, 3120
	s_mov_b32 m0, s12
	s_nop 0
	global_load_lds_dwordx4 v[42:43], off
	s_waitcnt vmcnt(0)
	s_barrier
	ds_read_b128 v[68:71], v44
	ds_read_b128 v[72:75], v45
	ds_read_b128 v[76:79], v44 offset:64
	ds_read_b128 v[80:83], v45 offset:64
	ds_read_b128 v[84:87], v44 offset:128
	ds_read_b128 v[88:91], v45 offset:128
	ds_read_b128 v[92:95], v44 offset:192
	ds_read_b128 v[96:99], v45 offset:192
	ds_read_b128 v[100:103], v44 offset:256
	ds_read_b128 v[104:107], v45 offset:256
	ds_read_b128 v[108:111], v44 offset:320
	ds_read_b128 v[112:115], v45 offset:320
	ds_read_b128 v[116:119], v44 offset:384
	ds_read_b128 v[120:123], v45 offset:384
	ds_read_b128 v[124:127], v44 offset:448
	ds_read_b128 v[128:131], v45 offset:448
	s_waitcnt lgkmcnt(14)
	v_mfma_f32_16x16x32_f16 v[0:3], v[72:75], v[68:71], v[0:3]
	s_waitcnt lgkmcnt(12)
	v_mfma_f32_16x16x32_f16 v[4:7], v[80:83], v[76:79], v[4:7]
	s_waitcnt lgkmcnt(10)
	v_mfma_f32_16x16x32_f16 v[0:3], v[88:91], v[84:87], v[0:3]
	s_waitcnt lgkmcnt(8)
	v_mfma_f32_16x16x32_f16 v[4:7], v[96:99], v[92:95], v[4:7]
	s_waitcnt lgkmcnt(6)
	v_mfma_f32_16x16x32_f16 v[0:3], v[104:107], v[100:103], v[0:3]
	s_waitcnt lgkmcnt(4)
	v_mfma_f32_16x16x32_f16 v[4:7], v[112:115], v[108:111], v[4:7]
	s_waitcnt lgkmcnt(2)
	v_mfma_f32_16x16x32_f16 v[0:3], v[120:123], v[116:119], v[0:3]
	s_waitcnt lgkmcnt(0)
	v_mfma_f32_16x16x32_f16 v[4:7], v[128:131], v[124:127], v[4:7]
	ds_read_b128 v[68:71], v44 offset:512
	ds_read_b128 v[72:75], v45 offset:512
	ds_read_b128 v[76:79], v44 offset:576
	ds_read_b128 v[80:83], v45 offset:576
	ds_read_b128 v[84:87], v44 offset:640
	ds_read_b128 v[88:91], v45 offset:640
	ds_read_b128 v[92:95], v44 offset:704
	ds_read_b128 v[96:99], v45 offset:704
	ds_read_b128 v[100:103], v44 offset:768
	ds_read_b128 v[104:107], v45 offset:768
	ds_read_b128 v[108:111], v44 offset:832
	ds_read_b128 v[112:115], v45 offset:832
	ds_read_b128 v[116:119], v44 offset:896
	ds_read_b128 v[120:123], v45 offset:896
	ds_read_b128 v[124:127], v44 offset:960
	ds_read_b128 v[128:131], v45 offset:960
	s_waitcnt lgkmcnt(14)
	v_mfma_f32_16x16x32_f16 v[0:3], v[72:75], v[68:71], v[0:3]
	s_waitcnt lgkmcnt(12)
	v_mfma_f32_16x16x32_f16 v[4:7], v[80:83], v[76:79], v[4:7]
	s_waitcnt lgkmcnt(10)
	v_mfma_f32_16x16x32_f16 v[0:3], v[88:91], v[84:87], v[0:3]
	s_waitcnt lgkmcnt(8)
	v_mfma_f32_16x16x32_f16 v[4:7], v[96:99], v[92:95], v[4:7]
	s_waitcnt lgkmcnt(6)
	v_mfma_f32_16x16x32_f16 v[0:3], v[104:107], v[100:103], v[0:3]
	s_waitcnt lgkmcnt(4)
	v_mfma_f32_16x16x32_f16 v[4:7], v[112:115], v[108:111], v[4:7]
	s_waitcnt lgkmcnt(2)
	v_mfma_f32_16x16x32_f16 v[0:3], v[120:123], v[116:119], v[0:3]
	s_waitcnt lgkmcnt(0)
	v_mfma_f32_16x16x32_f16 v[4:7], v[128:131], v[124:127], v[4:7]
	s_movk_i32 s10, 0x400
	v_lshl_add_u64 v[40:41], v[48:49], 0, s[10:11]
	v_lshl_add_u64 v[42:43], v[50:51], 0, s[10:11]
	s_movk_i32 s10, 0x800
	s_barrier
	s_mov_b32 m0, s7
	s_nop 0
	global_load_lds_dwordx4 v[40:41], off
	v_lshl_add_u64 v[40:41], v[40:41], 0, s[10:11]
	s_add_u32 s12, s7, 1040
	s_mov_b32 m0, s12
	s_nop 0
	global_load_lds_dwordx4 v[40:41], off
	v_lshl_add_u64 v[40:41], v[40:41], 0, s[10:11]
	s_add_u32 s12, s7, 2080
	s_mov_b32 m0, s12
	s_nop 0
	global_load_lds_dwordx4 v[40:41], off
	v_lshl_add_u64 v[40:41], v[40:41], 0, s[10:11]
	s_add_u32 s12, s7, 3120
	s_mov_b32 m0, s12
	s_nop 0
	global_load_lds_dwordx4 v[40:41], off
	v_lshl_add_u64 v[40:41], v[40:41], 0, s[10:11]
	s_add_u32 s12, s7, 4160
	s_mov_b32 m0, s12
	s_nop 0
	global_load_lds_dwordx4 v[40:41], off
	v_lshl_add_u64 v[40:41], v[40:41], 0, s[10:11]
	s_add_u32 s12, s7, 5200
	s_mov_b32 m0, s12
	s_nop 0
	global_load_lds_dwordx4 v[40:41], off
	v_lshl_add_u64 v[40:41], v[40:41], 0, s[10:11]
	s_add_u32 s12, s7, 6240
	s_mov_b32 m0, s12
	s_nop 0
	global_load_lds_dwordx4 v[40:41], off
	v_lshl_add_u64 v[40:41], v[40:41], 0, s[10:11]
	s_add_u32 s12, s7, 7280
	s_mov_b32 m0, s12
	s_nop 0
	global_load_lds_dwordx4 v[40:41], off
	s_mov_b32 m0, s8
	s_nop 0
	global_load_lds_dwordx4 v[42:43], off
	v_lshl_add_u64 v[42:43], v[42:43], 0, s[10:11]
	s_add_u32 s12, s8, 1040
	s_mov_b32 m0, s12
	s_nop 0
	global_load_lds_dwordx4 v[42:43], off
	v_lshl_add_u64 v[42:43], v[42:43], 0, s[10:11]
	s_add_u32 s12, s8, 2080
	s_mov_b32 m0, s12
	s_nop 0
	global_load_lds_dwordx4 v[42:43], off
	v_lshl_add_u64 v[42:43], v[42:43], 0, s[10:11]
	s_add_u32 s12, s8, 3120
	s_mov_b32 m0, s12
	s_nop 0
	global_load_lds_dwordx4 v[42:43], off
	s_waitcnt vmcnt(0)
	s_barrier
	ds_read_b128 v[68:71], v44
	ds_read_b128 v[72:75], v45
	ds_read_b128 v[76:79], v44 offset:64
	ds_read_b128 v[80:83], v45 offset:64
	ds_read_b128 v[84:87], v44 offset:128
	ds_read_b128 v[88:91], v45 offset:128
	ds_read_b128 v[92:95], v44 offset:192
	ds_read_b128 v[96:99], v45 offset:192
	ds_read_b128 v[100:103], v44 offset:256
	ds_read_b128 v[104:107], v45 offset:256
	ds_read_b128 v[108:111], v44 offset:320
	ds_read_b128 v[112:115], v45 offset:320
	ds_read_b128 v[116:119], v44 offset:384
	ds_read_b128 v[120:123], v45 offset:384
	ds_read_b128 v[124:127], v44 offset:448
	ds_read_b128 v[128:131], v45 offset:448
	s_waitcnt lgkmcnt(14)
	v_mfma_f32_16x16x32_f16 v[0:3], v[72:75], v[68:71], v[0:3]
	s_waitcnt lgkmcnt(12)
	v_mfma_f32_16x16x32_f16 v[4:7], v[80:83], v[76:79], v[4:7]
	s_waitcnt lgkmcnt(10)
	v_mfma_f32_16x16x32_f16 v[0:3], v[88:91], v[84:87], v[0:3]
	s_waitcnt lgkmcnt(8)
	v_mfma_f32_16x16x32_f16 v[4:7], v[96:99], v[92:95], v[4:7]
	s_waitcnt lgkmcnt(6)
	v_mfma_f32_16x16x32_f16 v[0:3], v[104:107], v[100:103], v[0:3]
	s_waitcnt lgkmcnt(4)
	v_mfma_f32_16x16x32_f16 v[4:7], v[112:115], v[108:111], v[4:7]
	s_waitcnt lgkmcnt(2)
	v_mfma_f32_16x16x32_f16 v[0:3], v[120:123], v[116:119], v[0:3]
	s_waitcnt lgkmcnt(0)
	v_mfma_f32_16x16x32_f16 v[4:7], v[128:131], v[124:127], v[4:7]
	ds_read_b128 v[68:71], v44 offset:512
	ds_read_b128 v[72:75], v45 offset:512
	ds_read_b128 v[76:79], v44 offset:576
	ds_read_b128 v[80:83], v45 offset:576
	ds_read_b128 v[84:87], v44 offset:640
	ds_read_b128 v[88:91], v45 offset:640
	ds_read_b128 v[92:95], v44 offset:704
	ds_read_b128 v[96:99], v45 offset:704
	ds_read_b128 v[100:103], v44 offset:768
	ds_read_b128 v[104:107], v45 offset:768
	ds_read_b128 v[108:111], v44 offset:832
	ds_read_b128 v[112:115], v45 offset:832
	ds_read_b128 v[116:119], v44 offset:896
	ds_read_b128 v[120:123], v45 offset:896
	ds_read_b128 v[124:127], v44 offset:960
	ds_read_b128 v[128:131], v45 offset:960
	s_waitcnt lgkmcnt(14)
	v_mfma_f32_16x16x32_f16 v[0:3], v[72:75], v[68:71], v[0:3]
	s_waitcnt lgkmcnt(12)
	v_mfma_f32_16x16x32_f16 v[4:7], v[80:83], v[76:79], v[4:7]
	s_waitcnt lgkmcnt(10)
	v_mfma_f32_16x16x32_f16 v[0:3], v[88:91], v[84:87], v[0:3]
	s_waitcnt lgkmcnt(8)
	v_mfma_f32_16x16x32_f16 v[4:7], v[96:99], v[92:95], v[4:7]
	s_waitcnt lgkmcnt(6)
	v_mfma_f32_16x16x32_f16 v[0:3], v[104:107], v[100:103], v[0:3]
	s_waitcnt lgkmcnt(4)
	v_mfma_f32_16x16x32_f16 v[4:7], v[112:115], v[108:111], v[4:7]
	s_waitcnt lgkmcnt(2)
	v_mfma_f32_16x16x32_f16 v[0:3], v[120:123], v[116:119], v[0:3]
	s_waitcnt lgkmcnt(0)
	v_mfma_f32_16x16x32_f16 v[4:7], v[128:131], v[124:127], v[4:7]
	s_nop 7
	s_lshl_b32 s7, s6, 1
	s_andn2_b32 s7, s7, 63
	s_addk_i32 s7, 0x4000
	v_or_b32_e32 v10, s7, v14
	s_lshl_b32 s8, s6, 5
	v_add_u32_e32 v10, v10, v15
	s_and_b32 s8, s8, 0x3e0
	v_ashrrev_i32_e32 v11, 31, v10
	v_pk_add_f32 v[2:3], v[2:3], v[6:7]
	v_pk_add_f32 v[0:1], v[0:1], v[4:5]
	v_or_b32_e32 v8, s8, v16
	v_cvt_pk_f16_f32 v3, v2, v3
	v_cvt_pk_f16_f32 v2, v0, v1
	v_lshlrev_b64 v[0:1], 12, v[10:11]
	v_and_b32_e32 v12, 3, v17
	v_lshl_add_u64 v[0:1], s[74:75], 0, v[0:1]
	v_lshlrev_b32_e32 v8, 1, v8
	v_lshl_add_u64 v[0:1], v[0:1], 0, v[8:9]
	v_lshlrev_b32_e32 v8, 3, v12
	s_add_i32 s6, s6, s13
	s_add_i32 s2, s2, s3
	s_add_i32 s4, s4, s5
	v_lshl_add_u64 v[0:1], v[0:1], 0, v[8:9]
	s_cmpk_gt_i32 s6, 0xff
	global_store_dwordx2 v[0:1], v[2:3], off
	s_cbranch_scc0 .LBB0_685

.LBB0_1301:
	s_barrier
	v_mov_b32_e32 v0, v154
	s_and_b32 s7, s2, 0xffffffc0
	s_addk_i32 s7, 0x4000
	v_ashrrev_i32_e32 v1, 3, v0
	v_and_b32_e32 v15, -16, v1
	v_and_b32_e32 v14, 15, v0
	v_lshrrev_b32_e32 v17, 4, v0
	v_lshrrev_b32_e32 v1, 2, v0
	v_and_b32_e32 v8, 48, v0
	v_add_u32_e32 v0, s7, v15
	v_or_b32_e32 v0, v0, v14
	v_and_b32_e32 v16, 16, v1
	v_ashrrev_i32_e32 v1, 31, v0
	s_and_b32 s8, s4, 0x3e0
	v_lshlrev_b64 v[0:1], 11, v[0:1]
	v_lshl_add_u64 v[10:11], s[14:15], 0, v[0:1]
	v_or3_b32 v0, s8, v16, v14
	v_lshlrev_b32_e32 v0, 11, v0
	v_mov_b32_e32 v1, v9
	v_lshl_add_u64 v[12:13], s[14:15], 0, v[0:1]
	s_movk_i32 s7, 0xffc0
	v_mov_b32_e32 v0, v9
	v_mov_b32_e32 v2, v9
	v_mov_b32_e32 v3, v9
	v_mov_b32_e32 v4, v9
	v_mov_b32_e32 v5, v9
	v_mov_b32_e32 v6, v9
	v_mov_b32_e32 v7, v9
	s_and_b32 s7, s2, 0xffffffc0
	s_addk_i32 s7, 0x4000
	v_lshrrev_b32_e32 v18, 6, v154
	v_and_b32_e32 v46, 63, v154
	v_lshlrev_b32_e32 v46, 4, v46
	v_mov_b32_e32 v47, 0
	v_readfirstlane_b32 s9, v18
	s_nop 3
	s_lshl_b32 s12, s9, 3
	s_add_u32 s12, s12, s7
	s_lshl_b32 s12, s12, 11
	s_add_u32 s10, s14, 0xd178000
	s_addc_u32 s11, s15, 0
	s_add_u32 s10, s10, s12
	s_addc_u32 s11, s11, 0
	v_lshl_add_u64 v[48:49], v[46:47], 0, s[10:11]
	s_lshl_b32 s12, s9, 2
	s_add_u32 s12, s12, s8
	s_lshl_b32 s12, s12, 11
	s_add_u32 s10, s14, 0x1100000
	s_addc_u32 s11, s15, 0
	s_add_u32 s10, s10, s12
	s_addc_u32 s11, s11, 0
	v_lshl_add_u64 v[50:51], v[46:47], 0, s[10:11]
	v_add_u32_e32 v18, v15, v14
	v_mul_u32_u24_e32 v18, 0x410, v18
	v_add_u32_e32 v44, v18, v8
	v_add_u32_e32 v19, v16, v14
	v_mul_u32_u24_e32 v19, 0x410, v19
	s_mov_b32 s12, 0x10400
	v_add3_u32 v45, v19, v8, s12
	s_mul_i32 s7, s9, 0x2080
	s_mul_i32 s8, s9, 0x1040
	s_add_u32 s8, s8, 0x10400
	s_mov_b32 s10, 0x800
	s_mov_b32 s11, 0
	v_mov_b32_e32 v40, v48
	v_mov_b32_e32 v41, v49
	v_mov_b32_e32 v42, v50
	v_mov_b32_e32 v43, v51
	s_mov_b32 m0, s7
	s_nop 0
	global_load_lds_dwordx4 v[40:41], off
	v_lshl_add_u64 v[40:41], v[40:41], 0, s[10:11]
	s_add_u32 s12, s7, 1040
	s_mov_b32 m0, s12
	s_nop 0
	global_load_lds_dwordx4 v[40:41], off
	v_lshl_add_u64 v[40:41], v[40:41], 0, s[10:11]
	s_add_u32 s12, s7, 2080
	s_mov_b32 m0, s12
	s_nop 0
	global_load_lds_dwordx4 v[40:41], off
	v_lshl_add_u64 v[40:41], v[40:41], 0, s[10:11]
	s_add_u32 s12, s7, 3120
	s_mov_b32 m0, s12
	s_nop 0
	global_load_lds_dwordx4 v[40:41], off
	v_lshl_add_u64 v[40:41], v[40:41], 0, s[10:11]
	s_add_u32 s12, s7, 4160
	s_mov_b32 m0, s12
	s_nop 0
	global_load_lds_dwordx4 v[40:41], off
	v_lshl_add_u64 v[40:41], v[40:41], 0, s[10:11]
	s_add_u32 s12, s7, 5200
	s_mov_b32 m0, s12
	s_nop 0
	global_load_lds_dwordx4 v[40:41], off
	v_lshl_add_u64 v[40:41], v[40:41], 0, s[10:11]
	s_add_u32 s12, s7, 6240
	s_mov_b32 m0, s12
	s_nop 0
	global_load_lds_dwordx4 v[40:41], off
	v_lshl_add_u64 v[40:41], v[40:41], 0, s[10:11]
	s_add_u32 s12, s7, 7280
	s_mov_b32 m0, s12
	s_nop 0
	global_load_lds_dwordx4 v[40:41], off
	s_mov_b32 m0, s8
	s_nop 0
	global_load_lds_dwordx4 v[42:43], off
	v_lshl_add_u64 v[42:43], v[42:43], 0, s[10:11]
	s_add_u32 s12, s8, 1040
	s_mov_b32 m0, s12
	s_nop 0
	global_load_lds_dwordx4 v[42:43], off
	v_lshl_add_u64 v[42:43], v[42:43], 0, s[10:11]
	s_add_u32 s12, s8, 2080
	s_mov_b32 m0, s12
	s_nop 0
	global_load_lds_dwordx4 v[42:43], off
	v_lshl_add_u64 v[42:43], v[42:43], 0, s[10:11]
	s_add_u32 s12, s8, 3120
	s_mov_b32 m0, s12
	s_nop 0
	global_load_lds_dwordx4 v[42:43], off
	s_waitcnt vmcnt(0)
	s_barrier
	ds_read_b128 v[68:71], v44
	ds_read_b128 v[72:75], v45
	ds_read_b128 v[76:79], v44 offset:64
	ds_read_b128 v[80:83], v45 offset:64
	ds_read_b128 v[84:87], v44 offset:128
	ds_read_b128 v[88:91], v45 offset:128
	ds_read_b128 v[92:95], v44 offset:192
	ds_read_b128 v[96:99], v45 offset:192
	ds_read_b128 v[100:103], v44 offset:256
	ds_read_b128 v[104:107], v45 offset:256
	ds_read_b128 v[108:111], v44 offset:320
	ds_read_b128 v[112:115], v45 offset:320
	ds_read_b128 v[116:119], v44 offset:384
	ds_read_b128 v[120:123], v45 offset:384
	ds_read_b128 v[124:127], v44 offset:448
	ds_read_b128 v[128:131], v45 offset:448
	s_waitcnt lgkmcnt(14)
	v_mfma_f32_16x16x32_f16 v[0:3], v[72:75], v[68:71], v[0:3]
	s_waitcnt lgkmcnt(12)
	v_mfma_f32_16x16x32_f16 v[4:7], v[80:83], v[76:79], v[4:7]
	s_waitcnt lgkmcnt(10)
	v_mfma_f32_16x16x32_f16 v[0:3], v[88:91], v[84:87], v[0:3]
	s_waitcnt lgkmcnt(8)
	v_mfma_f32_16x16x32_f16 v[4:7], v[96:99], v[92:95], v[4:7]
	s_waitcnt lgkmcnt(6)
	v_mfma_f32_16x16x32_f16 v[0:3], v[104:107], v[100:103], v[0:3]
	s_waitcnt lgkmcnt(4)
	v_mfma_f32_16x16x32_f16 v[4:7], v[112:115], v[108:111], v[4:7]
	s_waitcnt lgkmcnt(2)
	v_mfma_f32_16x16x32_f16 v[0:3], v[120:123], v[116:119], v[0:3]
	s_waitcnt lgkmcnt(0)
	v_mfma_f32_16x16x32_f16 v[4:7], v[128:131], v[124:127], v[4:7]
	ds_read_b128 v[68:71], v44 offset:512
	ds_read_b128 v[72:75], v45 offset:512
	ds_read_b128 v[76:79], v44 offset:576
	ds_read_b128 v[80:83], v45 offset:576
	ds_read_b128 v[84:87], v44 offset:640
	ds_read_b128 v[88:91], v45 offset:640
	ds_read_b128 v[92:95], v44 offset:704
	ds_read_b128 v[96:99], v45 offset:704
	ds_read_b128 v[100:103], v44 offset:768
	ds_read_b128 v[104:107], v45 offset:768
	ds_read_b128 v[108:111], v44 offset:832
	ds_read_b128 v[112:115], v45 offset:832
	ds_read_b128 v[116:119], v44 offset:896
	ds_read_b128 v[120:123], v45 offset:896
	ds_read_b128 v[124:127], v44 offset:960
	ds_read_b128 v[128:131], v45 offset:960
	s_waitcnt lgkmcnt(14)
	v_mfma_f32_16x16x32_f16 v[0:3], v[72:75], v[68:71], v[0:3]
	s_waitcnt lgkmcnt(12)
	v_mfma_f32_16x16x32_f16 v[4:7], v[80:83], v[76:79], v[4:7]
	s_waitcnt lgkmcnt(10)
	v_mfma_f32_16x16x32_f16 v[0:3], v[88:91], v[84:87], v[0:3]
	s_waitcnt lgkmcnt(8)
	v_mfma_f32_16x16x32_f16 v[4:7], v[96:99], v[92:95], v[4:7]
	s_waitcnt lgkmcnt(6)
	v_mfma_f32_16x16x32_f16 v[0:3], v[104:107], v[100:103], v[0:3]
	s_waitcnt lgkmcnt(4)
	v_mfma_f32_16x16x32_f16 v[4:7], v[112:115], v[108:111], v[4:7]
	s_waitcnt lgkmcnt(2)
	v_mfma_f32_16x16x32_f16 v[0:3], v[120:123], v[116:119], v[0:3]
	s_waitcnt lgkmcnt(0)
	v_mfma_f32_16x16x32_f16 v[4:7], v[128:131], v[124:127], v[4:7]
	s_movk_i32 s10, 0x400
	v_lshl_add_u64 v[40:41], v[48:49], 0, s[10:11]
	v_lshl_add_u64 v[42:43], v[50:51], 0, s[10:11]
	s_movk_i32 s10, 0x800
	s_barrier
	s_mov_b32 m0, s7
	s_nop 0
	global_load_lds_dwordx4 v[40:41], off
	v_lshl_add_u64 v[40:41], v[40:41], 0, s[10:11]
	s_add_u32 s12, s7, 1040
	s_mov_b32 m0, s12
	s_nop 0
	global_load_lds_dwordx4 v[40:41], off
	v_lshl_add_u64 v[40:41], v[40:41], 0, s[10:11]
	s_add_u32 s12, s7, 2080
	s_mov_b32 m0, s12
	s_nop 0
	global_load_lds_dwordx4 v[40:41], off
	v_lshl_add_u64 v[40:41], v[40:41], 0, s[10:11]
	s_add_u32 s12, s7, 3120
	s_mov_b32 m0, s12
	s_nop 0
	global_load_lds_dwordx4 v[40:41], off
	v_lshl_add_u64 v[40:41], v[40:41], 0, s[10:11]
	s_add_u32 s12, s7, 4160
	s_mov_b32 m0, s12
	s_nop 0
	global_load_lds_dwordx4 v[40:41], off
	v_lshl_add_u64 v[40:41], v[40:41], 0, s[10:11]
	s_add_u32 s12, s7, 5200
	s_mov_b32 m0, s12
	s_nop 0
	global_load_lds_dwordx4 v[40:41], off
	v_lshl_add_u64 v[40:41], v[40:41], 0, s[10:11]
	s_add_u32 s12, s7, 6240
	s_mov_b32 m0, s12
	s_nop 0
	global_load_lds_dwordx4 v[40:41], off
	v_lshl_add_u64 v[40:41], v[40:41], 0, s[10:11]
	s_add_u32 s12, s7, 7280
	s_mov_b32 m0, s12
	s_nop 0
	global_load_lds_dwordx4 v[40:41], off
	s_mov_b32 m0, s8
	s_nop 0
	global_load_lds_dwordx4 v[42:43], off
	v_lshl_add_u64 v[42:43], v[42:43], 0, s[10:11]
	s_add_u32 s12, s8, 1040
	s_mov_b32 m0, s12
	s_nop 0
	global_load_lds_dwordx4 v[42:43], off
	v_lshl_add_u64 v[42:43], v[42:43], 0, s[10:11]
	s_add_u32 s12, s8, 2080
	s_mov_b32 m0, s12
	s_nop 0
	global_load_lds_dwordx4 v[42:43], off
	v_lshl_add_u64 v[42:43], v[42:43], 0, s[10:11]
	s_add_u32 s12, s8, 3120
	s_mov_b32 m0, s12
	s_nop 0
	global_load_lds_dwordx4 v[42:43], off
	s_waitcnt vmcnt(0)
	s_barrier
	ds_read_b128 v[68:71], v44
	ds_read_b128 v[72:75], v45
	ds_read_b128 v[76:79], v44 offset:64
	ds_read_b128 v[80:83], v45 offset:64
	ds_read_b128 v[84:87], v44 offset:128
	ds_read_b128 v[88:91], v45 offset:128
	ds_read_b128 v[92:95], v44 offset:192
	ds_read_b128 v[96:99], v45 offset:192
	ds_read_b128 v[100:103], v44 offset:256
	ds_read_b128 v[104:107], v45 offset:256
	ds_read_b128 v[108:111], v44 offset:320
	ds_read_b128 v[112:115], v45 offset:320
	ds_read_b128 v[116:119], v44 offset:384
	ds_read_b128 v[120:123], v45 offset:384
	ds_read_b128 v[124:127], v44 offset:448
	ds_read_b128 v[128:131], v45 offset:448
	s_waitcnt lgkmcnt(14)
	v_mfma_f32_16x16x32_f16 v[0:3], v[72:75], v[68:71], v[0:3]
	s_waitcnt lgkmcnt(12)
	v_mfma_f32_16x16x32_f16 v[4:7], v[80:83], v[76:79], v[4:7]
	s_waitcnt lgkmcnt(10)
	v_mfma_f32_16x16x32_f16 v[0:3], v[88:91], v[84:87], v[0:3]
	s_waitcnt lgkmcnt(8)
	v_mfma_f32_16x16x32_f16 v[4:7], v[96:99], v[92:95], v[4:7]
	s_waitcnt lgkmcnt(6)
	v_mfma_f32_16x16x32_f16 v[0:3], v[104:107], v[100:103], v[0:3]
	s_waitcnt lgkmcnt(4)
	v_mfma_f32_16x16x32_f16 v[4:7], v[112:115], v[108:111], v[4:7]
	s_waitcnt lgkmcnt(2)
	v_mfma_f32_16x16x32_f16 v[0:3], v[120:123], v[116:119], v[0:3]
	s_waitcnt lgkmcnt(0)
	v_mfma_f32_16x16x32_f16 v[4:7], v[128:131], v[124:127], v[4:7]
	ds_read_b128 v[68:71], v44 offset:512
	ds_read_b128 v[72:75], v45 offset:512
	ds_read_b128 v[76:79], v44 offset:576
	ds_read_b128 v[80:83], v45 offset:576
	ds_read_b128 v[84:87], v44 offset:640
	ds_read_b128 v[88:91], v45 offset:640
	ds_read_b128 v[92:95], v44 offset:704
	ds_read_b128 v[96:99], v45 offset:704
	ds_read_b128 v[100:103], v44 offset:768
	ds_read_b128 v[104:107], v45 offset:768
	ds_read_b128 v[108:111], v44 offset:832
	ds_read_b128 v[112:115], v45 offset:832
	ds_read_b128 v[116:119], v44 offset:896
	ds_read_b128 v[120:123], v45 offset:896
	ds_read_b128 v[124:127], v44 offset:960
	ds_read_b128 v[128:131], v45 offset:960
	s_waitcnt lgkmcnt(14)
	v_mfma_f32_16x16x32_f16 v[0:3], v[72:75], v[68:71], v[0:3]
	s_waitcnt lgkmcnt(12)
	v_mfma_f32_16x16x32_f16 v[4:7], v[80:83], v[76:79], v[4:7]
	s_waitcnt lgkmcnt(10)
	v_mfma_f32_16x16x32_f16 v[0:3], v[88:91], v[84:87], v[0:3]
	s_waitcnt lgkmcnt(8)
	v_mfma_f32_16x16x32_f16 v[4:7], v[96:99], v[92:95], v[4:7]
	s_waitcnt lgkmcnt(6)
	v_mfma_f32_16x16x32_f16 v[0:3], v[104:107], v[100:103], v[0:3]
	s_waitcnt lgkmcnt(4)
	v_mfma_f32_16x16x32_f16 v[4:7], v[112:115], v[108:111], v[4:7]
	s_waitcnt lgkmcnt(2)
	v_mfma_f32_16x16x32_f16 v[0:3], v[120:123], v[116:119], v[0:3]
	s_waitcnt lgkmcnt(0)
	v_mfma_f32_16x16x32_f16 v[4:7], v[128:131], v[124:127], v[4:7]
	s_nop 7
	s_lshl_b32 s7, s6, 1
	s_andn2_b32 s7, s7, 63
	s_addk_i32 s7, 0x4000
	v_or_b32_e32 v10, s7, v14
	s_lshl_b32 s8, s6, 5
	v_add_u32_e32 v10, v10, v15
	s_and_b32 s8, s8, 0x3e0
	v_ashrrev_i32_e32 v11, 31, v10
	v_pk_add_f32 v[2:3], v[2:3], v[6:7]
	v_pk_add_f32 v[0:1], v[0:1], v[4:5]
	v_or_b32_e32 v8, s8, v16
	v_cvt_pk_f16_f32 v3, v2, v3
	v_cvt_pk_f16_f32 v2, v0, v1
	v_lshlrev_b64 v[0:1], 12, v[10:11]
	v_and_b32_e32 v12, 3, v17
	v_lshl_add_u64 v[0:1], s[74:75], 0, v[0:1]
	v_lshlrev_b32_e32 v8, 1, v8
	v_lshl_add_u64 v[0:1], v[0:1], 0, v[8:9]
	v_lshlrev_b32_e32 v8, 3, v12
	s_add_i32 s6, s6, s13
	s_add_i32 s2, s2, s3
	s_add_i32 s4, s4, s5
	v_lshl_add_u64 v[0:1], v[0:1], 0, v[8:9]
	s_cmpk_gt_i32 s6, 0xff
	global_store_dwordx2 v[0:1], v[2:3], off offset:2048
	s_cbranch_scc0 .LBB0_1301
